# P0 weight transposer: batched scale loads; P2 post-proj row loop unrolled with all loads issued up front
# speedup vs baseline: 1.0133x; 1.0053x over previous
; DI void prologue(const Params& p, LAS unsigned char* lds, int tid, int lane, int wave) {
;     ...
;     __syncthreads();
;     for (int it = gw; it < I11; it += NGW) {
;         int ii, ksi, dK, dN, dNpad, dldt, dmap, i0; size_t off;
;         if (it < I0)       { ii = 2;  ksi = 0;  off = OFF_WIN;  dK = 2048; dN = 2672; dNpad = 2816; dldt = 2048; dmap = 0; i0 = 0; }
;         else if (it < I1)  { ii = 5;  ksi = 3;  off = OFF_WUQ;  dK = 512;  dN = 1536; dNpad = 1536; dldt = 512;  dmap = 1; i0 = I0; }
;         else if (it < I2)  { ii = 6;  ksi = 4;  off = OFF_WK;   dK = 256;  dN = 1024; dNpad = 1024; dldt = 256;  dmap = 0; i0 = I1; }
;         else if (it < I3)  { ii = 7;  ksi = 4;  off = OFF_WV;   dK = 256;  dN = 1024; dNpad = 1024; dldt = 256;  dmap = 0; i0 = I2; }
;         else if (it < I4)  { ii = 14; ksi = 0;  off = OFF_WO;   dK = 2048; dN = 2048; dNpad = 2048; dldt = 2048; dmap = 0; i0 = I3; }
;         else if (it < I5)  { ii = 16; ksi = 15; off = OFF_WGU;  dK = 2048; dN = 5632; dNpad = 5632; dldt = 2048; dmap = 2; i0 = I4; }
;         else if (it < I6)  { ii = 17; ksi = 15; off = OFF_WGU;  dK = 2048; dN = 5632; dNpad = 5632; dldt = 2048; dmap = 3; i0 = I5; }
;         else if (it < I7)  { ii = 18; ksi = 0;  off = OFF_WD;   dK = 5632; dN = 2048; dNpad = 2048; dldt = 5632; dmap = 0; i0 = I6; }
;         else if (it < I8)  { ii = 10; ksi = 0;  off = OFF_WC1K; dK = 2048; dN = 128;  dNpad = 256;  dldt = 2048; dmap = 0; i0 = I7; }
;         else if (it < I9)  { ii = 12; ksi = 0;  off = OFF_WC1V; dK = 2048; dN = 128;  dNpad = 256;  dldt = 2048; dmap = 0; i0 = I8; }
;         else if (it < I10) { ii = 11; ksi = 0;  off = OFF_WC2K; dK = 128;  dN = 64;   dNpad = 256;  dldt = 256;  dmap = 0; i0 = I9; }
;         else               { ii = 13; ksi = 0;  off = OFF_WC2V; dK = 128;  dN = 64;   dNpad = 256;  dldt = 256;  dmap = 0; i0 = I10; }
;         transpose_item(PTg[ii], PTg[ksi], (bf16_t*)(ws + off), dK, dN, dNpad, dldt, dmap, scr, it - i0, lane);
.LBB0_4:
	s_or_b64 exec, exec, s[0:1]
	s_lshl_b32 s1, s86, 3
	s_ashr_i32 s0, s2, 6
	s_lshl_b32 s88, s64, 3
	v_and_b32_e32 v1, 63, v2
	s_add_i32 s6, s0, s1
	s_cmpk_gt_i32 s6, 0x59bf
	v_lshlrev_b32_e32 v36, 3, v1
	v_writelane_b32 v234, s1, 10
	s_waitcnt lgkmcnt(0)
	s_barrier
	s_cbranch_scc1 .LBB0_111
	s_lshl_b32 s0, s0, 14
	v_lshlrev_b32_e32 v4, 2, v1
	s_add_i32 s0, s0, 0
	v_lshrrev_b32_e32 v3, 3, v1
	v_and_b32_e32 v37, 28, v4
	v_and_b32_e32 v4, 56, v36
	v_lshl_add_u32 v5, v37, 2, s0
	v_mul_u32_u24_e32 v6, 0x84, v3
	v_mul_u32_u24_e32 v7, 0x84, v4
	v_lshlrev_b32_e32 v8, 2, v3
	s_mov_b32 s9, 0
	v_or_b32_e32 v46, 8, v3
	v_or_b32_e32 v47, 16, v3
	v_or_b32_e32 v48, 24, v3
	v_bfe_u32 v49, v1, 3, 2
	v_mov_b32_e32 v39, 0
	v_add3_u32 v50, s0, v7, v8
	v_or_b32_e32 v51, 4, v3
	s_mov_b32 s7, 0x2e980000
	s_movk_i32 s13, 0xa680
	s_add_i32 s28, 0, 0x26a00
	v_add_u32_e32 v52, v5, v6
	s_movk_i32 s29, 0xffc8
	s_mov_b32 s30, 0x2aaaaaab
	s_movk_i32 s31, 0xc0
	s_movk_i32 s33, 0xa0
	s_movk_i32 s34, 0x7f
	s_movk_i32 s35, 0xff80
	s_movk_i32 s40, 0xff41
	v_lshlrev_b32_e32 v38, 1, v4
	s_movk_i32 s41, 0xffd8
	s_movk_i32 s42, 0xffe8
	s_mov_b32 s43, s6
	v_mov_b32_e32 v112, 1.0
	v_mov_b32_e32 v114, 1.0
	v_mov_b32_e32 v116, 1.0
	v_mov_b32_e32 v118, 1.0
	v_mov_b32_e32 v120, 1.0
	v_mov_b32_e32 v122, 1.0
	v_mov_b32_e32 v124, 1.0
	v_mov_b32_e32 v126, 1.0
	s_branch .LBB0_9

; #define LAS __attribute__((address_space(3)))
; DI void transpose_item(const float* dW, const float* dks, bf16_t* dWT, int dK, int dN, int dNpad, int dldt, int dmap, LAS float* scr, int item, int lane) {
;     const int nblk = dNpad / 32, kb = item / nblk, nb = item - kb * nblk, k0 = 64 * kb, n0 = 32 * nb;
;     f32x4 ld[8];
; #pragma unroll
;     for (int i = 0; i < 8; ++i) {
;         const int kk = 8 * i + (lane >> 3), k = k0 + kk, n = n0 + 4 * (lane & 7);
;         ld[i] = (f32x4){0.f, 0.f, 0.f, 0.f};
;         if (k < dK && n < dN) { ld[i] = *(const f32x4*)(dW + (size_t)k * dN + n); if (dks) ld[i] = ld[i] * dks[k]; }
.LBB0_28:
	s_lshl_b32 s2, s2, 3
	v_cvt_f32_ubyte0_e32 v5, s1
	s_add_i32 s2, s28, s2
	v_rcp_iflag_f32_e32 v7, v5
	v_mov_b32_e32 v4, s2
	s_lshl_b32 s2, s3, 3
	s_add_i32 s2, s28, s2
	v_mov_b32_e32 v6, s2
	ds_read_b64 v[4:5], v4
	ds_read_b64 v[40:41], v6
	v_mul_f32_e32 v6, 0x4f7ffffe, v7
	v_cvt_u32_f32_e32 v6, v6
	s_sub_i32 s11, 0, s1
	s_add_i32 s0, s0, s43
	s_abs_i32 s3, s0
	v_readfirstlane_b32 s22, v6
	s_mul_i32 s11, s11, s22
	s_mul_hi_u32 s11, s22, s11
	s_add_i32 s22, s22, s11
	s_mul_hi_u32 s11, s3, s22
	s_mul_i32 s22, s11, s1
	s_sub_i32 s3, s3, s22
	s_ashr_i32 s2, s0, 31
	s_add_i32 s22, s11, 1
	s_sub_i32 s26, s3, s1
	s_cmp_ge_u32 s3, s1
	s_cselect_b32 s11, s22, s11
	s_cselect_b32 s3, s26, s3
	s_add_i32 s22, s11, 1
	s_cmp_ge_u32 s3, s1
	s_cselect_b32 s3, s22, s11
	s_xor_b32 s3, s3, s2
	s_sub_i32 s2, s3, s2
	s_mul_i32 s1, s1, s2
	s_sub_i32 s0, s0, s1
	s_lshl_b32 s22, s2, 6
	s_lshl_b32 s11, s0, 5
	v_or_b32_e32 v42, s22, v3
	v_or_b32_e32 v6, s11, v37
	v_cmp_gt_i32_e64 s[2:3], s23, v6
	v_cmp_gt_i32_e32 vcc, s44, v42
	v_ashrrev_i32_e32 v7, 31, v6
	s_and_b64 s[46:47], vcc, s[2:3]
	s_waitcnt lgkmcnt(0)
	v_cmp_ne_u64_e32 vcc, 0, v[40:41]
	v_lshl_add_u64 v[44:45], v[6:7], 2, v[4:5]
	v_mov_b32_e32 v4, 0
	v_cndmask_b32_e64 v5, 0, 1, vcc
	v_cmp_ne_u32_e64 s[0:1], 1, v5
	v_mov_b32_e32 v8, 0
	v_mov_b32_e32 v9, 0
	v_mov_b32_e32 v10, 0
	v_mov_b32_e32 v11, 0
	s_and_saveexec_b64 s[26:27], s[46:47]
	s_cbranch_execz .LBB0_31
	v_mad_u64_u32 v[6:7], s[46:47], v42, s23, 0
	v_ashrrev_i32_e32 v43, 31, v42
	v_mov_b32_e32 v8, v7
	v_mad_u64_u32 v[8:9], s[46:47], v43, s23, v[8:9]
	v_mov_b32_e32 v7, v8
	v_lshl_add_u64 v[6:7], v[6:7], 2, v[44:45]
	flat_load_dwordx4 v[8:11], v[6:7]
	s_and_b64 vcc, exec, s[0:1]
	s_cbranch_vccnz .LBB0_31
	v_lshl_add_u64 v[6:7], v[42:43], 2, v[40:41]
	flat_load_dword v112, v[6:7]
.LBB0_31:
	s_or_b64 exec, exec, s[26:27]
	v_or_b32_e32 v12, 8, v42
	v_cmp_gt_i32_e32 vcc, s44, v12
	s_and_b64 s[46:47], vcc, s[2:3]
	v_mov_b32_e32 v5, 0
	v_mov_b32_e32 v6, 0
	v_mov_b32_e32 v7, 0
	s_and_saveexec_b64 s[26:27], s[46:47]
	s_cbranch_execz .LBB0_34
	v_mad_u64_u32 v[4:5], s[46:47], v12, s23, 0
	v_ashrrev_i32_e32 v7, 31, v12
	v_mov_b32_e32 v6, v5
	v_mad_u64_u32 v[6:7], s[46:47], v7, s23, v[6:7]
	v_mov_b32_e32 v5, v6
	v_lshl_add_u64 v[4:5], v[4:5], 2, v[44:45]
	flat_load_dwordx4 v[4:7], v[4:5]
	s_and_b64 vcc, exec, s[0:1]
	s_cbranch_vccnz .LBB0_34
	v_ashrrev_i32_e32 v43, 31, v42
	v_lshl_add_u64 v[12:13], v[42:43], 2, v[40:41]
	flat_load_dword v114, v[12:13] offset:32
.LBB0_34:
	s_or_b64 exec, exec, s[26:27]
	v_or_b32_e32 v13, 16, v42
	v_cmp_gt_i32_e32 vcc, s44, v13
	s_and_b64 s[46:47], vcc, s[2:3]
	v_mov_b32_e32 v12, 0
	v_mov_b32_e32 v16, 0
	v_mov_b32_e32 v17, 0
	v_mov_b32_e32 v18, 0
	v_mov_b32_e32 v19, 0
	s_and_saveexec_b64 s[26:27], s[46:47]
	s_cbranch_execz .LBB0_37
	v_mad_u64_u32 v[14:15], s[46:47], v13, s23, 0
	v_ashrrev_i32_e32 v17, 31, v13
	v_mov_b32_e32 v16, v15
	v_mad_u64_u32 v[16:17], s[46:47], v17, s23, v[16:17]
	v_mov_b32_e32 v15, v16
	v_lshl_add_u64 v[14:15], v[14:15], 2, v[44:45]
	flat_load_dwordx4 v[16:19], v[14:15]
	s_and_b64 vcc, exec, s[0:1]
	s_cbranch_vccnz .LBB0_37
	v_ashrrev_i32_e32 v43, 31, v42
	v_lshl_add_u64 v[14:15], v[42:43], 2, v[40:41]
	flat_load_dword v116, v[14:15] offset:64
.LBB0_37:
	s_or_b64 exec, exec, s[26:27]
	v_or_b32_e32 v20, 24, v42
	v_cmp_gt_i32_e32 vcc, s44, v20
	s_and_b64 s[46:47], vcc, s[2:3]
	v_mov_b32_e32 v13, 0
	v_mov_b32_e32 v14, 0
	v_mov_b32_e32 v15, 0
	s_and_saveexec_b64 s[26:27], s[46:47]
	s_cbranch_execz .LBB0_40
	v_mad_u64_u32 v[12:13], s[46:47], v20, s23, 0
	v_ashrrev_i32_e32 v15, 31, v20
	v_mov_b32_e32 v14, v13
	v_mad_u64_u32 v[14:15], s[46:47], v15, s23, v[14:15]
	v_mov_b32_e32 v13, v14
	v_lshl_add_u64 v[12:13], v[12:13], 2, v[44:45]
	flat_load_dwordx4 v[12:15], v[12:13]
	s_and_b64 vcc, exec, s[0:1]
	s_cbranch_vccnz .LBB0_40
	v_ashrrev_i32_e32 v43, 31, v42
	v_lshl_add_u64 v[20:21], v[42:43], 2, v[40:41]
	flat_load_dword v118, v[20:21] offset:96
.LBB0_40:
	s_or_b64 exec, exec, s[26:27]
	v_or_b32_e32 v21, 32, v42
	v_cmp_gt_i32_e32 vcc, s44, v21
	s_and_b64 s[46:47], vcc, s[2:3]
	v_mov_b32_e32 v20, 0
	v_mov_b32_e32 v24, 0
	v_mov_b32_e32 v25, 0
	v_mov_b32_e32 v26, 0
	v_mov_b32_e32 v27, 0
	s_and_saveexec_b64 s[26:27], s[46:47]
	s_cbranch_execz .LBB0_43
	v_mad_u64_u32 v[22:23], s[46:47], v21, s23, 0
	v_ashrrev_i32_e32 v25, 31, v21
	v_mov_b32_e32 v24, v23
	v_mad_u64_u32 v[24:25], s[46:47], v25, s23, v[24:25]
	v_mov_b32_e32 v23, v24
	v_lshl_add_u64 v[22:23], v[22:23], 2, v[44:45]
	flat_load_dwordx4 v[24:27], v[22:23]
	s_and_b64 vcc, exec, s[0:1]
	s_cbranch_vccnz .LBB0_43
	v_ashrrev_i32_e32 v43, 31, v42
	v_lshl_add_u64 v[22:23], v[42:43], 2, v[40:41]
	flat_load_dword v120, v[22:23] offset:128
; #define LAS __attribute__((address_space(3)))
; DI unsigned pk2(float lo, float hi) { const f32x2 v = {lo, hi}; const hwbf16x2 b = __builtin_convertvector(v, hwbf16x2); return __builtin_bit_cast(unsigned, b); }
; #define LDS_WAIT() asm volatile("s_waitcnt lgkmcnt(0)" ::: "memory")
; DI void transpose_item(const float* dW, const float* dks, bf16_t* dWT, int dK, int dN, int dNpad, int dldt, int dmap, LAS float* scr, int item, int lane) {
;     ...
;     f32x4 ld[8];
; #pragma unroll
;     for (int i = 0; i < 8; ++i) {
;         const int kk = 8 * i + (lane >> 3), k = k0 + kk, n = n0 + 4 * (lane & 7);
;         ld[i] = (f32x4){0.f, 0.f, 0.f, 0.f};
;         if (k < dK && n < dN) { ld[i] = *(const f32x4*)(dW + (size_t)k * dN + n); if (dks) ld[i] = ld[i] * dks[k]; }
;     }
; #pragma unroll
;     for (int i = 0; i < 8; ++i) {
;         const int kk = 8 * i + (lane >> 3); LAS float* d = scr + kk * 33 + 4 * (lane & 7);
;         d[0] = ld[i].x; d[1] = ld[i].y; d[2] = ld[i].z; d[3] = ld[i].w;
;     }
;     LDS_WAIT();
;     const int c = lane & 7;
; #pragma unroll
;     for (int j = 0; j < 4; ++j) {
;         const int n = (lane >> 3) + 8 * j; const LAS float* s = scr + (8 * c) * 33 + n;
;         u32x4 o; o.x = pk2(s[0 * 33], s[1 * 33]); o.y = pk2(s[2 * 33], s[3 * 33]); o.z = pk2(s[4 * 33], s[5 * 33]); o.w = pk2(s[6 * 33], s[7 * 33]);
;         *(u32x4*)(dWT + (size_t)map_row(dmap, n0 + n) * dldt + k0 + 8 * c) = o;
.LBB0_43:
	s_or_b64 exec, exec, s[26:27]
	v_or_b32_e32 v28, 40, v42
	v_cmp_gt_i32_e32 vcc, s44, v28
	s_and_b64 s[46:47], vcc, s[2:3]
	v_mov_b32_e32 v21, 0
	v_mov_b32_e32 v22, 0
	v_mov_b32_e32 v23, 0
	s_and_saveexec_b64 s[26:27], s[46:47]
	s_cbranch_execz .LBB0_46
	v_mad_u64_u32 v[20:21], s[46:47], v28, s23, 0
	v_ashrrev_i32_e32 v23, 31, v28
	v_mov_b32_e32 v22, v21
	v_mad_u64_u32 v[22:23], s[46:47], v23, s23, v[22:23]
	v_mov_b32_e32 v21, v22
	v_lshl_add_u64 v[20:21], v[20:21], 2, v[44:45]
	flat_load_dwordx4 v[20:23], v[20:21]
	s_and_b64 vcc, exec, s[0:1]
	s_cbranch_vccnz .LBB0_46
	v_ashrrev_i32_e32 v43, 31, v42
	v_lshl_add_u64 v[28:29], v[42:43], 2, v[40:41]
	flat_load_dword v122, v[28:29] offset:160
.LBB0_46:
	s_or_b64 exec, exec, s[26:27]
	v_or_b32_e32 v29, 48, v42
	v_cmp_gt_i32_e32 vcc, s44, v29
	s_and_b64 s[46:47], vcc, s[2:3]
	v_mov_b32_e32 v28, 0
	v_mov_b32_e32 v32, 0
	v_mov_b32_e32 v33, 0
	v_mov_b32_e32 v34, 0
	v_mov_b32_e32 v35, 0
	s_and_saveexec_b64 s[26:27], s[46:47]
	s_cbranch_execz .LBB0_49
	v_mad_u64_u32 v[30:31], s[46:47], v29, s23, 0
	v_ashrrev_i32_e32 v33, 31, v29
	v_mov_b32_e32 v32, v31
	v_mad_u64_u32 v[32:33], s[46:47], v33, s23, v[32:33]
	v_mov_b32_e32 v31, v32
	v_lshl_add_u64 v[30:31], v[30:31], 2, v[44:45]
	flat_load_dwordx4 v[32:35], v[30:31]
	s_and_b64 vcc, exec, s[0:1]
	s_cbranch_vccnz .LBB0_49
	v_ashrrev_i32_e32 v43, 31, v42
	v_lshl_add_u64 v[30:31], v[42:43], 2, v[40:41]
	flat_load_dword v124, v[30:31] offset:192
.LBB0_49:
	s_or_b64 exec, exec, s[26:27]
	v_or_b32_e32 v43, 56, v42
	v_cmp_gt_i32_e32 vcc, s44, v43
	s_and_b64 s[26:27], vcc, s[2:3]
	v_mov_b32_e32 v29, 0
	v_mov_b32_e32 v30, 0
	v_mov_b32_e32 v31, 0
	s_and_saveexec_b64 s[2:3], s[26:27]
	s_cbranch_execz .LBB0_52
	v_mad_u64_u32 v[28:29], s[26:27], v43, s23, 0
	v_ashrrev_i32_e32 v31, 31, v43
	v_mov_b32_e32 v30, v29
	v_mad_u64_u32 v[30:31], s[26:27], v31, s23, v[30:31]
	v_mov_b32_e32 v29, v30
	v_lshl_add_u64 v[28:29], v[28:29], 2, v[44:45]
	flat_load_dwordx4 v[28:31], v[28:29]
	s_and_b64 vcc, exec, s[0:1]
	s_cbranch_vccnz .LBB0_52
	v_ashrrev_i32_e32 v43, 31, v42
	v_lshl_add_u64 v[40:41], v[42:43], 2, v[40:41]
	flat_load_dword v126, v[40:41] offset:224
.LBB0_52:
	s_or_b64 exec, exec, s[2:3]
	s_waitcnt vmcnt(0) lgkmcnt(0)
	s_and_b64 vcc, exec, s[0:1]
	s_cbranch_vccnz .Ltr_noscale
	v_pk_mul_f32 v[10:11], v[10:11], v[112:113] op_sel_hi:[1,0]
	v_pk_mul_f32 v[8:9], v[8:9], v[112:113] op_sel_hi:[1,0]
	v_pk_mul_f32 v[6:7], v[6:7], v[114:115] op_sel_hi:[1,0]
	v_pk_mul_f32 v[4:5], v[4:5], v[114:115] op_sel_hi:[1,0]
	v_pk_mul_f32 v[18:19], v[18:19], v[116:117] op_sel_hi:[1,0]
	v_pk_mul_f32 v[16:17], v[16:17], v[116:117] op_sel_hi:[1,0]
	v_pk_mul_f32 v[14:15], v[14:15], v[118:119] op_sel_hi:[1,0]
	v_pk_mul_f32 v[12:13], v[12:13], v[118:119] op_sel_hi:[1,0]
	v_pk_mul_f32 v[26:27], v[26:27], v[120:121] op_sel_hi:[1,0]
	v_pk_mul_f32 v[24:25], v[24:25], v[120:121] op_sel_hi:[1,0]
	v_pk_mul_f32 v[22:23], v[22:23], v[122:123] op_sel_hi:[1,0]
	v_pk_mul_f32 v[20:21], v[20:21], v[122:123] op_sel_hi:[1,0]
	v_pk_mul_f32 v[34:35], v[34:35], v[124:125] op_sel_hi:[1,0]
	v_pk_mul_f32 v[32:33], v[32:33], v[124:125] op_sel_hi:[1,0]
	v_pk_mul_f32 v[30:31], v[30:31], v[126:127] op_sel_hi:[1,0]
	v_pk_mul_f32 v[28:29], v[28:29], v[126:127] op_sel_hi:[1,0]
.Ltr_noscale:
	ds_write2_b32 v52, v8, v9 offset1:1
	ds_write2_b32 v52, v10, v11 offset0:2 offset1:3
	v_add_u32_e32 v8, 0x420, v52
	ds_write2_b32 v8, v4, v5 offset1:1
	v_add_u32_e32 v4, 0x428, v52
	ds_write2_b32 v4, v6, v7 offset1:1
	v_add_u32_e32 v4, 0x840, v52
	ds_write2_b32 v4, v16, v17 offset1:1
	v_add_u32_e32 v4, 0x848, v52
	ds_write2_b32 v4, v18, v19 offset1:1
	v_add_u32_e32 v4, 0xc60, v52
	ds_write2_b32 v4, v12, v13 offset1:1
	v_add_u32_e32 v4, 0xc68, v52
	ds_write2_b32 v4, v14, v15 offset1:1
	v_add_u32_e32 v4, 0x1080, v52
	ds_write2_b32 v4, v24, v25 offset1:1
	v_add_u32_e32 v4, 0x1088, v52
	ds_write2_b32 v4, v26, v27 offset1:1
	v_add_u32_e32 v4, 0x14a0, v52
	ds_write2_b32 v4, v20, v21 offset1:1
	v_add_u32_e32 v4, 0x14a8, v52
	ds_write2_b32 v4, v22, v23 offset1:1
	v_add_u32_e32 v4, 0x18c0, v52
	ds_write2_b32 v4, v32, v33 offset1:1
	v_add_u32_e32 v4, 0x18c8, v52
	ds_write2_b32 v4, v34, v35 offset1:1
	v_add_u32_e32 v4, 0x1ce0, v52
	ds_write2_b32 v4, v28, v29 offset1:1
	v_add_u32_e32 v4, 0x1ce8, v52
	ds_write2_b32 v4, v30, v31 offset1:1
	s_waitcnt lgkmcnt(0)
	ds_read2_b32 v[6:7], v50 offset1:33
	ds_read2_b32 v[8:9], v50 offset0:66 offset1:99
	ds_read2_b32 v[10:11], v50 offset0:132 offset1:165
	ds_read2_b32 v[12:13], v50 offset0:198 offset1:231
	v_or_b32_e32 v4, s11, v3
	s_cmp_lt_i32 s8, 2
	s_mov_b64 s[0:1], -1
	s_cbranch_scc1 .LBB0_58
	s_cmp_gt_i32 s8, 2
	v_lshlrev_b32_e32 v5, 1, v4
	s_cbranch_scc0 .LBB0_55
	v_and_or_b32 v14, v5, s29, v51
	s_mov_b64 s[0:1], 0

; #define LAS __attribute__((address_space(3)))
; DI void postproj_tile(const Params& p, LAS unsigned char* lds, int tile, int tid, int lane, int wave) {
;     ...
; #pragma unroll
;     for (int i = 0; i < 4; ++i) {
;         const int q = tid + 512 * i, mat = q >> 10, r = (q >> 4) & 63, ch = q & 15;
;         const u32x4 v = *(const u32x4*)(PROJ + (size_t)(tok0 + r) * NPROJ + (mat ? 2496 : 2240) + 8 * ch);
;         *(LAS u32x4*)(tl + (mat * 64 + r) * 136 + 8 * ch) = v;
;     }
;     __syncthreads();
;     bf16_t* VST = (bf16_t*)(ws + OFF_VST); bf16_t* VWT = (bf16_t*)(ws + OFF_VWT);
; #pragma unroll
;     for (int i = 0; i < 4; ++i) {
;         const int q = tid + 512 * i, mat = q >> 10, c = (q >> 3) & 127, j8 = q & 7;
;         unsigned e[8];
; #pragma unroll
;         for (int k = 0; k < 8; ++k) e[k] = tl[(mat * 64 + 8 * j8 + k) * 136 + c];
;         u32x4 o; o.x = e[0] | (e[1] << 16); o.y = e[2] | (e[3] << 16); o.z = e[4] | (e[5] << 16); o.w = e[6] | (e[7] << 16);
;         const int g = c >> 6, d = c & 63;
;         bf16_t* dst = (mat ? VWT : VST) + ((size_t)((b * 2 + g) * 64 + d)) * S_ + s0 + 8 * j8;
;         *(u32x4*)dst = o;
;     }
.LBB0_272:
	s_lshl_b32 s7, s29, 6
	v_or_b32_e32 v27, s7, v15
	v_mov_b64_e32 v[32:33], s[44:45]
	v_or_b32_e32 v29, s7, v17
	v_mad_i64_i32 v[32:33], s[24:25], v27, s28, v[32:33]
	v_mad_i64_i32 v[36:37], s[24:25], v29, s28, v[2:3]
	v_mov_b32_e32 v29, v1
	v_lshl_add_u64 v[34:35], v[32:33], 0, v[0:1]
	v_mov_b32_e32 v27, v1
	v_lshl_add_u64 v[32:33], v[32:33], 0, v[28:29]
	v_lshl_add_u64 v[34:35], v[34:35], 0, v[26:27]
	v_lshl_add_u64 v[32:33], v[32:33], 0, v[26:27]
	v_or_b32_e32 v27, s7, v19
	global_load_dwordx4 v[68:71], v[34:35], off
	global_load_dwordx4 v[72:75], v[36:37], off
	v_mad_i64_i32 v[34:35], s[24:25], v27, s28, v[4:5]
	global_load_dwordx4 v[76:79], v[32:33], off
	global_load_dwordx4 v[80:83], v[34:35], off
	s_and_b32 s34, s29, 0xffffff80
	v_or_b32_e32 v42, s34, v44
	v_or_b32_e32 v84, s34, v45
	v_ashrrev_i32_e32 v43, 31, v42
	s_bfe_u32 s18, s0, 0x70006
	s_lshl_b32 s35, s29, 7
	v_ashrrev_i32_e32 v85, 31, v84
	v_lshlrev_b64 v[88:89], 14, v[42:43]
	v_lshl_add_u32 v27, s18, 11, v53
	s_lshl_b32 s38, s18, 6
	s_and_b32 s18, s35, 0x3f80
	v_lshlrev_b64 v[42:43], 14, v[84:85]
	v_lshl_add_u64 v[84:85], v[6:7], 0, v[88:89]
	s_and_b32 s30, s12, 0xffffc000
	s_ashr_i32 s7, s6, 31
	v_mad_i64_i32 v[32:33], s[24:25], s6, v66, v[22:23]
	v_mad_i64_i32 v[34:35], s[24:25], s6, v66, v[24:25]
	v_mov_b32_e32 v31, v1
	v_lshl_add_u64 v[84:85], v[84:85], 0, s[18:19]
	s_lshl_b64 s[24:25], s[6:7], 2
	s_lshl_b64 s[26:27], s[6:7], 7
	s_or_b32 s7, s38, s30
	v_lshl_add_u64 v[84:85], v[84:85], 0, v[30:31]
	v_add_u32_e32 v86, s7, v54
	v_ashrrev_i32_e32 v87, 31, v86
	v_lshl_add_u64 v[90:91], v[8:9], 0, v[42:43]
	v_lshlrev_b64 v[42:43], 7, v[86:87]
	v_lshl_add_u64 v[86:87], v[90:91], 0, s[18:19]
	v_lshl_add_u64 v[86:87], v[86:87], 0, v[30:31]
	s_mul_hi_i32 s31, s6, 0x1600
	s_mul_i32 s33, s6, 0x1600
	v_mov_b32_e32 v37, s31
	v_or_b32_e32 v36, s33, v14
	v_mov_b32_e32 v39, s31
	v_or_b32_e32 v38, s33, v16
	v_lshl_add_u64 v[40:41], v[20:21], 0, s[26:27]
	v_or_b32_e32 v42, v18, v42
	s_mov_b32 s7, 0
	s_waitcnt vmcnt(3)
	ds_write_b128 v55, v[68:71]
	s_waitcnt vmcnt(2)
	ds_write_b128 v56, v[72:75]
	s_waitcnt vmcnt(1)
	ds_write_b128 v57, v[76:79]
	s_waitcnt vmcnt(0)
	ds_write_b128 v58, v[80:83]
	s_waitcnt lgkmcnt(0)
	s_barrier
	ds_read_u16 v29, v59
	ds_read_u16 v67, v59 offset:272
	ds_read_u16 v69, v59 offset:544
	ds_read_u16 v70, v59 offset:816
	ds_read_u16 v71, v59 offset:1088
	ds_read_u16 v72, v59 offset:1360
	ds_read_u16 v73, v59 offset:1632
	ds_read_u16 v74, v59 offset:1904
	ds_read_u16 v75, v60
	ds_read_u16 v76, v60 offset:272
	ds_read_u16 v77, v60 offset:544
	ds_read_u16 v78, v60 offset:816
	ds_read_u16 v79, v60 offset:1088
	ds_read_u16 v80, v60 offset:1360
	ds_read_u16 v81, v60 offset:1632
	ds_read_u16 v82, v60 offset:1904
	s_waitcnt lgkmcnt(14)
	v_lshl_or_b32 v68, v67, 16, v29
	s_waitcnt lgkmcnt(12)
	v_lshl_or_b32 v69, v70, 16, v69
	s_waitcnt lgkmcnt(10)
	v_lshl_or_b32 v70, v72, 16, v71
	s_waitcnt lgkmcnt(8)
	v_lshl_or_b32 v71, v74, 16, v73
	global_store_dwordx4 v[84:85], v[68:71], off
	s_waitcnt lgkmcnt(6)
	v_lshl_or_b32 v72, v76, 16, v75
	s_waitcnt lgkmcnt(4)
	v_lshl_or_b32 v73, v78, 16, v77
	ds_read_u16 v29, v61
	ds_read_u16 v67, v61 offset:272
	ds_read_u16 v69, v61 offset:544
	ds_read_u16 v70, v61 offset:816
	ds_read_u16 v71, v61 offset:1088
	ds_read_u16 v76, v61 offset:1360
	ds_read_u16 v77, v61 offset:1632
	ds_read_u16 v78, v61 offset:1904
	s_waitcnt lgkmcnt(10)
	v_lshl_or_b32 v74, v80, 16, v79
	s_waitcnt lgkmcnt(8)
	v_lshl_or_b32 v75, v82, 16, v81
	global_store_dwordx4 v[86:87], v[72:75], off
	s_waitcnt lgkmcnt(6)
	v_lshl_or_b32 v68, v67, 16, v29
	s_waitcnt lgkmcnt(4)
	v_lshl_or_b32 v69, v70, 16, v69
	v_lshl_add_u64 v[72:73], v[10:11], 0, v[88:89]
	v_lshl_add_u64 v[72:73], v[72:73], 0, s[18:19]
	s_waitcnt lgkmcnt(2)
	v_lshl_or_b32 v70, v76, 16, v71
	s_waitcnt lgkmcnt(0)
	v_lshl_or_b32 v71, v78, 16, v77
	v_lshl_add_u64 v[72:73], v[72:73], 0, v[30:31]
	ds_read_u16 v29, v62
	ds_read_u16 v67, v62 offset:272
	ds_read_u16 v74, v62 offset:544
	ds_read_u16 v75, v62 offset:816
	ds_read_u16 v76, v62 offset:1088
	ds_read_u16 v77, v62 offset:1360
	ds_read_u16 v78, v62 offset:1632
	ds_read_u16 v79, v62 offset:1904
	global_store_dwordx4 v[72:73], v[68:71], off
	v_or_b32_e32 v72, s34, v46
	v_ashrrev_i32_e32 v73, 31, v72
	v_lshlrev_b64 v[72:73], 14, v[72:73]
	v_lshl_add_u64 v[72:73], v[12:13], 0, v[72:73]
	v_lshl_add_u64 v[72:73], v[72:73], 0, s[18:19]
	s_waitcnt lgkmcnt(6)
	v_lshl_or_b32 v68, v67, 16, v29
	s_waitcnt lgkmcnt(4)
	v_lshl_or_b32 v69, v75, 16, v74
	s_waitcnt lgkmcnt(2)
	v_lshl_or_b32 v70, v77, 16, v76
	s_waitcnt lgkmcnt(0)
; DI unsigned pk2(float lo, float hi) { const f32x2 v = {lo, hi}; const hwbf16x2 b = __builtin_convertvector(v, hwbf16x2); return __builtin_bit_cast(unsigned, b); }
; DI float frsq(float x) { return __builtin_amdgcn_rsqf(x); }
; DI void postproj_tile(const Params& p, LAS unsigned char* lds, int tile, int tid, int lane, int wave) {
;     ...
;     for (int rr = 0; rr < 8; ++rr) {
;         const int r = wave * 8 + rr, tok = tok0 + r, s = s0 + r;
;         const bf16_t* pr = PROJ + (size_t)tok * NPROJ;
;         const u32x4 a = *(const u32x4*)(pr + 8 * lane);
;         float sq = 0.f;
;         { float f; f = bflo(a.x); sq += f * f; f = bfhi(a.x); sq += f * f; f = bflo(a.y); sq += f * f; f = bfhi(a.y); sq += f * f;
;           f = bflo(a.z); sq += f * f; f = bfhi(a.z); sq += f * f; f = bflo(a.w); sq += f * f; f = bfhi(a.w); sq += f * f; }
;         sq = wave_sum(sq);
;         const u32x2 c2 = *(const u32x2*)(pr + 512 + 4 * lane);
;         float sk = 0.f;
;         { float f; f = bflo(c2.x); sk += f * f; f = bfhi(c2.x); sk += f * f; f = bflo(c2.y); sk += f * f; f = bfhi(c2.y); sk += f * f; }
;         sk = wave_sum(sk);
;         if (lane == 0) { RSQ[tok] = frsq(sq * (1.0f / 512.0f) + 1e-6f); RSKV[tok] = frsq(sk * (1.0f / 256.0f) + 1e-6f); }
;         if (lane < 32) {
;             const float x1 = bf2f(pr[768 + lane]), x2 = bf2f(pr[800 + lane]);
;             const float cs = COS[s * 32 + lane], sn = SIN[s * 32 + lane];
;             *(unsigned*)(KROPE + (size_t)tok * 64 + 2 * lane) = pk2(x1 * cs - x2 * sn, x1 * sn + x2 * cs);
;         }
;         const int g = lane >> 5, d = (2 * lane) & 63;
;         const unsigned kc2 = *(const unsigned*)(pr + 1856 + 2 * lane);
;         *(unsigned*)(KCg + ((size_t)((b * 2 + g) * S_ + s)) * 64 + d) = kc2;
;         const unsigned vc2 = *(const unsigned*)(pr + 1984 + 2 * lane);
;         *(unsigned*)(VCg + ((size_t)((b * 2 + g) * S_ + s)) * 64 + d) = vc2;
	v_lshl_or_b32 v71, v79, 16, v78
	v_lshl_add_u64 v[72:73], v[72:73], 0, v[30:31]
	global_store_dwordx4 v[72:73], v[68:71], off
	v_lshl_add_u64 v[236:237], s[62:63], 0, v[34:35]
	v_lshl_add_u64 v[238:239], s[62:63], 0, v[32:33]
	global_load_dwordx4 v[96:99], v[236:237], off
	global_load_dwordx2 v[128:129], v[238:239], off
	v_lshl_add_u64 v[236:237], v[236:237], 0, s[22:23]
	v_lshl_add_u64 v[238:239], v[238:239], 0, s[22:23]
	global_load_dwordx4 v[100:103], v[236:237], off
	global_load_dwordx2 v[130:131], v[238:239], off
	v_lshl_add_u64 v[236:237], v[236:237], 0, s[22:23]
	v_lshl_add_u64 v[238:239], v[238:239], 0, s[22:23]
	global_load_dwordx4 v[104:107], v[236:237], off
	global_load_dwordx2 v[132:133], v[238:239], off
	v_lshl_add_u64 v[236:237], v[236:237], 0, s[22:23]
	v_lshl_add_u64 v[238:239], v[238:239], 0, s[22:23]
	global_load_dwordx4 v[108:111], v[236:237], off
	global_load_dwordx2 v[134:135], v[238:239], off
	v_lshl_add_u64 v[236:237], v[236:237], 0, s[22:23]
	v_lshl_add_u64 v[238:239], v[238:239], 0, s[22:23]
	global_load_dwordx4 v[112:115], v[236:237], off
	global_load_dwordx2 v[136:137], v[238:239], off
	v_lshl_add_u64 v[236:237], v[236:237], 0, s[22:23]
	v_lshl_add_u64 v[238:239], v[238:239], 0, s[22:23]
	global_load_dwordx4 v[116:119], v[236:237], off
	global_load_dwordx2 v[138:139], v[238:239], off
	v_lshl_add_u64 v[236:237], v[236:237], 0, s[22:23]
	v_lshl_add_u64 v[238:239], v[238:239], 0, s[22:23]
	global_load_dwordx4 v[120:123], v[236:237], off
	global_load_dwordx2 v[140:141], v[238:239], off
	v_lshl_add_u64 v[236:237], v[236:237], 0, s[22:23]
	v_lshl_add_u64 v[238:239], v[238:239], 0, s[22:23]
	global_load_dwordx4 v[124:127], v[236:237], off
	global_load_dwordx2 v[142:143], v[238:239], off
	s_and_saveexec_b64 s[26:27], s[4:5]
	v_lshl_add_u64 v[240:241], s[62:63], 0, v[38:39]
	v_ashrrev_i32_e32 v243, 31, v27
	v_mov_b32_e32 v242, v27
	v_add_co_u32_e32 v240, vcc, 0x8000000, v240
	v_lshlrev_b64 v[244:245], 2, v[242:243]
	s_nop 1
	v_addc_co_u32_e32 v241, vcc, 0, v241, vcc
	v_lshl_add_u64 v[246:247], s[10:11], 0, v[244:245]
	v_lshl_add_u64 v[248:249], s[14:15], 0, v[244:245]
	global_load_ushort v194, v[240:241], off offset:1600
	global_load_ushort v186, v[240:241], off offset:1536
	global_load_dword v202, v[248:249], off offset:0
	global_load_dword v218, v[246:247], off offset:0
	v_lshl_add_u64 v[240:241], v[240:241], 0, s[22:23]
	global_load_ushort v195, v[240:241], off offset:1600
	global_load_ushort v187, v[240:241], off offset:1536
	global_load_dword v204, v[248:249], off offset:128
	global_load_dword v220, v[246:247], off offset:128
	v_lshl_add_u64 v[240:241], v[240:241], 0, s[22:23]
	global_load_ushort v196, v[240:241], off offset:1600
	global_load_ushort v188, v[240:241], off offset:1536
	global_load_dword v206, v[248:249], off offset:256
	global_load_dword v222, v[246:247], off offset:256
	v_lshl_add_u64 v[240:241], v[240:241], 0, s[22:23]
	global_load_ushort v197, v[240:241], off offset:1600
	global_load_ushort v189, v[240:241], off offset:1536
	global_load_dword v208, v[248:249], off offset:384
	global_load_dword v224, v[246:247], off offset:384
	v_lshl_add_u64 v[240:241], v[240:241], 0, s[22:23]
	global_load_ushort v198, v[240:241], off offset:1600
	global_load_ushort v190, v[240:241], off offset:1536
	global_load_dword v210, v[248:249], off offset:512
	global_load_dword v226, v[246:247], off offset:512
	v_lshl_add_u64 v[240:241], v[240:241], 0, s[22:23]
	global_load_ushort v199, v[240:241], off offset:1600
	global_load_ushort v191, v[240:241], off offset:1536
	global_load_dword v212, v[248:249], off offset:640
	global_load_dword v228, v[246:247], off offset:640
	v_lshl_add_u64 v[240:241], v[240:241], 0, s[22:23]
	global_load_ushort v200, v[240:241], off offset:1600
	global_load_ushort v192, v[240:241], off offset:1536
	global_load_dword v214, v[248:249], off offset:768
	global_load_dword v230, v[246:247], off offset:768
	v_lshl_add_u64 v[240:241], v[240:241], 0, s[22:23]
	global_load_ushort v201, v[240:241], off offset:1600
	global_load_ushort v193, v[240:241], off offset:1536
	global_load_dword v216, v[248:249], off offset:896
	global_load_dword v232, v[246:247], off offset:896
	s_or_b64 exec, exec, s[26:27]
	v_lshl_add_u64 v[250:251], s[62:63], 0, v[36:37]
	s_nop 0
	v_add_co_u32_e32 v250, vcc, 0x8000000, v250
	s_nop 1
	v_addc_co_u32_e32 v251, vcc, 0, v251, vcc
	global_load_dword v170, v[250:251], off offset:3712
	global_load_dword v178, v[250:251], off offset:3968
	v_lshl_add_u64 v[250:251], v[250:251], 0, s[22:23]
	global_load_dword v171, v[250:251], off offset:3712
	global_load_dword v179, v[250:251], off offset:3968
	v_lshl_add_u64 v[250:251], v[250:251], 0, s[22:23]
	global_load_dword v172, v[250:251], off offset:3712
	global_load_dword v180, v[250:251], off offset:3968
	v_lshl_add_u64 v[250:251], v[250:251], 0, s[22:23]
	global_load_dword v173, v[250:251], off offset:3712
	global_load_dword v181, v[250:251], off offset:3968
	v_lshl_add_u64 v[250:251], v[250:251], 0, s[22:23]
	global_load_dword v174, v[250:251], off offset:3712
	global_load_dword v182, v[250:251], off offset:3968
	v_lshl_add_u64 v[250:251], v[250:251], 0, s[22:23]
	global_load_dword v175, v[250:251], off offset:3712
	global_load_dword v183, v[250:251], off offset:3968
	v_lshl_add_u64 v[250:251], v[250:251], 0, s[22:23]
	global_load_dword v176, v[250:251], off offset:3712
	global_load_dword v184, v[250:251], off offset:3968
	v_lshl_add_u64 v[250:251], v[250:251], 0, s[22:23]
	global_load_dword v177, v[250:251], off offset:3712
	global_load_dword v185, v[250:251], off offset:3968
	s_waitcnt vmcnt(62)
; DI void postproj_tile(const Params& p, LAS unsigned char* lds, int tile, int tid, int lane, int wave) {
;     ...
;         const u32x4 a = *(const u32x4*)(pr + 8 * lane);
;         float sq = 0.f;
;         { float f; f = bflo(a.x); sq += f * f; f = bfhi(a.x); sq += f * f; f = bflo(a.y); sq += f * f; f = bfhi(a.y); sq += f * f;
;           f = bflo(a.z); sq += f * f; f = bfhi(a.z); sq += f * f; f = bflo(a.w); sq += f * f; f = bfhi(a.w); sq += f * f; }
;         sq = wave_sum(sq);
;         const u32x2 c2 = *(const u32x2*)(pr + 512 + 4 * lane);
;         float sk = 0.f;
;         { float f; f = bflo(c2.x); sk += f * f; f = bfhi(c2.x); sk += f * f; f = bflo(c2.y); sk += f * f; f = bfhi(c2.y); sk += f * f; }
;         sk = wave_sum(sk);
	v_and_b32_e32 v236, 0xffff0000, v96
	v_lshlrev_b32_e32 v68, 16, v96
	v_mul_f32_e32 v236, v236, v236
	v_lshlrev_b32_e32 v69, 16, v97
	v_fmac_f32_e32 v236, v68, v68
	v_and_b32_e32 v70, 0xffff0000, v97
	v_fmac_f32_e32 v236, v69, v69
	v_lshlrev_b32_e32 v68, 16, v98
	v_fmac_f32_e32 v236, v70, v70
	v_and_b32_e32 v69, 0xffff0000, v98
	v_fmac_f32_e32 v236, v68, v68
	v_lshlrev_b32_e32 v70, 16, v99
	v_fmac_f32_e32 v236, v69, v69
	v_and_b32_e32 v68, 0xffff0000, v99
	v_fmac_f32_e32 v236, v70, v70
	v_fmac_f32_e32 v236, v68, v68
	v_and_b32_e32 v244, 0xffff0000, v128
	v_lshlrev_b32_e32 v69, 16, v128
	v_mul_f32_e32 v244, v244, v244
	v_lshlrev_b32_e32 v70, 16, v129
	v_fmac_f32_e32 v244, v69, v69
	v_and_b32_e32 v68, 0xffff0000, v129
	v_fmac_f32_e32 v244, v70, v70
	v_fmac_f32_e32 v244, v68, v68
	s_waitcnt vmcnt(60)
	v_and_b32_e32 v237, 0xffff0000, v100
	v_lshlrev_b32_e32 v68, 16, v100
	v_mul_f32_e32 v237, v237, v237
	v_lshlrev_b32_e32 v69, 16, v101
	v_fmac_f32_e32 v237, v68, v68
	v_and_b32_e32 v70, 0xffff0000, v101
	v_fmac_f32_e32 v237, v69, v69
	v_lshlrev_b32_e32 v68, 16, v102
	v_fmac_f32_e32 v237, v70, v70
	v_and_b32_e32 v69, 0xffff0000, v102
	v_fmac_f32_e32 v237, v68, v68
	v_lshlrev_b32_e32 v70, 16, v103
	v_fmac_f32_e32 v237, v69, v69
	v_and_b32_e32 v68, 0xffff0000, v103
	v_fmac_f32_e32 v237, v70, v70
	v_fmac_f32_e32 v237, v68, v68
	v_and_b32_e32 v245, 0xffff0000, v130
	v_lshlrev_b32_e32 v69, 16, v130
	v_mul_f32_e32 v245, v245, v245
	v_lshlrev_b32_e32 v70, 16, v131
	v_fmac_f32_e32 v245, v69, v69
	v_and_b32_e32 v68, 0xffff0000, v131
	v_fmac_f32_e32 v245, v70, v70
	v_fmac_f32_e32 v245, v68, v68
	s_waitcnt vmcnt(58)
	v_and_b32_e32 v238, 0xffff0000, v104
	v_lshlrev_b32_e32 v68, 16, v104
	v_mul_f32_e32 v238, v238, v238
	v_lshlrev_b32_e32 v69, 16, v105
	v_fmac_f32_e32 v238, v68, v68
	v_and_b32_e32 v70, 0xffff0000, v105
	v_fmac_f32_e32 v238, v69, v69
	v_lshlrev_b32_e32 v68, 16, v106
	v_fmac_f32_e32 v238, v70, v70
	v_and_b32_e32 v69, 0xffff0000, v106
	v_fmac_f32_e32 v238, v68, v68
	v_lshlrev_b32_e32 v70, 16, v107
	v_fmac_f32_e32 v238, v69, v69
	v_and_b32_e32 v68, 0xffff0000, v107
	v_fmac_f32_e32 v238, v70, v70
	v_fmac_f32_e32 v238, v68, v68
	v_and_b32_e32 v246, 0xffff0000, v132
	v_lshlrev_b32_e32 v69, 16, v132
	v_mul_f32_e32 v246, v246, v246
	v_lshlrev_b32_e32 v70, 16, v133
	v_fmac_f32_e32 v246, v69, v69
	v_and_b32_e32 v68, 0xffff0000, v133
	v_fmac_f32_e32 v246, v70, v70
	v_fmac_f32_e32 v246, v68, v68
	s_waitcnt vmcnt(56)
	v_and_b32_e32 v239, 0xffff0000, v108
	v_lshlrev_b32_e32 v68, 16, v108
	v_mul_f32_e32 v239, v239, v239
	v_lshlrev_b32_e32 v69, 16, v109
	v_fmac_f32_e32 v239, v68, v68
	v_and_b32_e32 v70, 0xffff0000, v109
	v_fmac_f32_e32 v239, v69, v69
	v_lshlrev_b32_e32 v68, 16, v110
	v_fmac_f32_e32 v239, v70, v70
	v_and_b32_e32 v69, 0xffff0000, v110
	v_fmac_f32_e32 v239, v68, v68
	v_lshlrev_b32_e32 v70, 16, v111
	v_fmac_f32_e32 v239, v69, v69
	v_and_b32_e32 v68, 0xffff0000, v111
	v_fmac_f32_e32 v239, v70, v70
	v_fmac_f32_e32 v239, v68, v68
	v_and_b32_e32 v247, 0xffff0000, v134
	v_lshlrev_b32_e32 v69, 16, v134
	v_mul_f32_e32 v247, v247, v247
	v_lshlrev_b32_e32 v70, 16, v135
	v_fmac_f32_e32 v247, v69, v69
	v_and_b32_e32 v68, 0xffff0000, v135
	v_fmac_f32_e32 v247, v70, v70
	v_fmac_f32_e32 v247, v68, v68
	s_waitcnt vmcnt(54)
	v_and_b32_e32 v240, 0xffff0000, v112
	v_lshlrev_b32_e32 v68, 16, v112
	v_mul_f32_e32 v240, v240, v240
	v_lshlrev_b32_e32 v69, 16, v113
	v_fmac_f32_e32 v240, v68, v68
	v_and_b32_e32 v70, 0xffff0000, v113
	v_fmac_f32_e32 v240, v69, v69
	v_lshlrev_b32_e32 v68, 16, v114
	v_fmac_f32_e32 v240, v70, v70
	v_and_b32_e32 v69, 0xffff0000, v114
	v_fmac_f32_e32 v240, v68, v68
	v_lshlrev_b32_e32 v70, 16, v115
	v_fmac_f32_e32 v240, v69, v69
	v_and_b32_e32 v68, 0xffff0000, v115
	v_fmac_f32_e32 v240, v70, v70
	v_fmac_f32_e32 v240, v68, v68
	v_and_b32_e32 v248, 0xffff0000, v136
	v_lshlrev_b32_e32 v69, 16, v136
	v_mul_f32_e32 v248, v248, v248
	v_lshlrev_b32_e32 v70, 16, v137
	v_fmac_f32_e32 v248, v69, v69
	v_and_b32_e32 v68, 0xffff0000, v137
	v_fmac_f32_e32 v248, v70, v70
	v_fmac_f32_e32 v248, v68, v68
	s_waitcnt vmcnt(52)
	v_and_b32_e32 v241, 0xffff0000, v116
	v_lshlrev_b32_e32 v68, 16, v116
	v_mul_f32_e32 v241, v241, v241
	v_lshlrev_b32_e32 v69, 16, v117
	v_fmac_f32_e32 v241, v68, v68
	v_and_b32_e32 v70, 0xffff0000, v117
	v_fmac_f32_e32 v241, v69, v69
	v_lshlrev_b32_e32 v68, 16, v118
	v_fmac_f32_e32 v241, v70, v70
	v_and_b32_e32 v69, 0xffff0000, v118
	v_fmac_f32_e32 v241, v68, v68
	v_lshlrev_b32_e32 v70, 16, v119
	v_fmac_f32_e32 v241, v69, v69
	v_and_b32_e32 v68, 0xffff0000, v119
	v_fmac_f32_e32 v241, v70, v70
	v_fmac_f32_e32 v241, v68, v68
	v_and_b32_e32 v249, 0xffff0000, v138
	v_lshlrev_b32_e32 v69, 16, v138
	v_mul_f32_e32 v249, v249, v249
	v_lshlrev_b32_e32 v70, 16, v139
	v_fmac_f32_e32 v249, v69, v69
	v_and_b32_e32 v68, 0xffff0000, v139
	v_fmac_f32_e32 v249, v70, v70
	v_fmac_f32_e32 v249, v68, v68
	s_waitcnt vmcnt(50)
	v_and_b32_e32 v242, 0xffff0000, v120
	v_lshlrev_b32_e32 v68, 16, v120
	v_mul_f32_e32 v242, v242, v242
	v_lshlrev_b32_e32 v69, 16, v121
	v_fmac_f32_e32 v242, v68, v68
	v_and_b32_e32 v70, 0xffff0000, v121
	v_fmac_f32_e32 v242, v69, v69
	v_lshlrev_b32_e32 v68, 16, v122
	v_fmac_f32_e32 v242, v70, v70
	v_and_b32_e32 v69, 0xffff0000, v122
	v_fmac_f32_e32 v242, v68, v68
	v_lshlrev_b32_e32 v70, 16, v123
	v_fmac_f32_e32 v242, v69, v69
	v_and_b32_e32 v68, 0xffff0000, v123
	v_fmac_f32_e32 v242, v70, v70
	v_fmac_f32_e32 v242, v68, v68
	v_and_b32_e32 v250, 0xffff0000, v140
	v_lshlrev_b32_e32 v69, 16, v140
	v_mul_f32_e32 v250, v250, v250
	v_lshlrev_b32_e32 v70, 16, v141
	v_fmac_f32_e32 v250, v69, v69
	v_and_b32_e32 v68, 0xffff0000, v141
	v_fmac_f32_e32 v250, v70, v70
	v_fmac_f32_e32 v250, v68, v68
	s_waitcnt vmcnt(48)
; DI float wave_sum(float v) {
; #pragma unroll
;     for (int o = 1; o < 64; o <<= 1) v += __shfl_xor(v, o);
;     return v;
; }
; DI void postproj_tile(const Params& p, LAS unsigned char* lds, int tile, int tid, int lane, int wave) {
;     ...
;         sq = wave_sum(sq);
;         const u32x2 c2 = *(const u32x2*)(pr + 512 + 4 * lane);
;         float sk = 0.f;
;         { float f; f = bflo(c2.x); sk += f * f; f = bfhi(c2.x); sk += f * f; f = bflo(c2.y); sk += f * f; f = bfhi(c2.y); sk += f * f; }
;         sk = wave_sum(sk);
	v_and_b32_e32 v243, 0xffff0000, v124
	v_lshlrev_b32_e32 v68, 16, v124
	v_mul_f32_e32 v243, v243, v243
	v_lshlrev_b32_e32 v69, 16, v125
	v_fmac_f32_e32 v243, v68, v68
	v_and_b32_e32 v70, 0xffff0000, v125
	v_fmac_f32_e32 v243, v69, v69
	v_lshlrev_b32_e32 v68, 16, v126
	v_fmac_f32_e32 v243, v70, v70
	v_and_b32_e32 v69, 0xffff0000, v126
	v_fmac_f32_e32 v243, v68, v68
	v_lshlrev_b32_e32 v70, 16, v127
	v_fmac_f32_e32 v243, v69, v69
	v_and_b32_e32 v68, 0xffff0000, v127
	v_fmac_f32_e32 v243, v70, v70
	v_fmac_f32_e32 v243, v68, v68
	v_and_b32_e32 v251, 0xffff0000, v142
	v_lshlrev_b32_e32 v69, 16, v142
	v_mul_f32_e32 v251, v251, v251
	v_lshlrev_b32_e32 v70, 16, v143
	v_fmac_f32_e32 v251, v69, v69
	v_and_b32_e32 v68, 0xffff0000, v143
	v_fmac_f32_e32 v251, v70, v70
	v_fmac_f32_e32 v251, v68, v68
	ds_bpermute_b32 v104, v47, v244
	ds_bpermute_b32 v96, v47, v236
	ds_bpermute_b32 v105, v47, v245
	ds_bpermute_b32 v97, v47, v237
	ds_bpermute_b32 v106, v47, v246
	ds_bpermute_b32 v98, v47, v238
	ds_bpermute_b32 v107, v47, v247
	ds_bpermute_b32 v99, v47, v239
	ds_bpermute_b32 v108, v47, v248
	ds_bpermute_b32 v100, v47, v240
	ds_bpermute_b32 v109, v47, v249
	ds_bpermute_b32 v101, v47, v241
	ds_bpermute_b32 v110, v47, v250
	ds_bpermute_b32 v102, v47, v242
	ds_bpermute_b32 v111, v47, v251
	ds_bpermute_b32 v103, v47, v243
	s_waitcnt lgkmcnt(15)
	v_add_f32_e32 v244, v244, v104
	s_waitcnt lgkmcnt(14)
	v_add_f32_e32 v236, v236, v96
	s_waitcnt lgkmcnt(13)
	v_add_f32_e32 v245, v245, v105
	s_waitcnt lgkmcnt(12)
	v_add_f32_e32 v237, v237, v97
	s_waitcnt lgkmcnt(11)
	v_add_f32_e32 v246, v246, v106
	s_waitcnt lgkmcnt(10)
	v_add_f32_e32 v238, v238, v98
	s_waitcnt lgkmcnt(9)
	v_add_f32_e32 v247, v247, v107
	s_waitcnt lgkmcnt(8)
	v_add_f32_e32 v239, v239, v99
	s_waitcnt lgkmcnt(7)
	v_add_f32_e32 v248, v248, v108
	s_waitcnt lgkmcnt(6)
	v_add_f32_e32 v240, v240, v100
	s_waitcnt lgkmcnt(5)
	v_add_f32_e32 v249, v249, v109
	s_waitcnt lgkmcnt(4)
	v_add_f32_e32 v241, v241, v101
	s_waitcnt lgkmcnt(3)
	v_add_f32_e32 v250, v250, v110
	s_waitcnt lgkmcnt(2)
	v_add_f32_e32 v242, v242, v102
	s_waitcnt lgkmcnt(1)
	v_add_f32_e32 v251, v251, v111
	s_waitcnt lgkmcnt(0)
	v_add_f32_e32 v243, v243, v103
	ds_bpermute_b32 v104, v48, v244
	ds_bpermute_b32 v96, v48, v236
	ds_bpermute_b32 v105, v48, v245
	ds_bpermute_b32 v97, v48, v237
	ds_bpermute_b32 v106, v48, v246
	ds_bpermute_b32 v98, v48, v238
	ds_bpermute_b32 v107, v48, v247
	ds_bpermute_b32 v99, v48, v239
	ds_bpermute_b32 v108, v48, v248
	ds_bpermute_b32 v100, v48, v240
	ds_bpermute_b32 v109, v48, v249
	ds_bpermute_b32 v101, v48, v241
	ds_bpermute_b32 v110, v48, v250
	ds_bpermute_b32 v102, v48, v242
	ds_bpermute_b32 v111, v48, v251
	ds_bpermute_b32 v103, v48, v243
	s_waitcnt lgkmcnt(15)
	v_add_f32_e32 v244, v244, v104
	s_waitcnt lgkmcnt(14)
	v_add_f32_e32 v236, v236, v96
	s_waitcnt lgkmcnt(13)
	v_add_f32_e32 v245, v245, v105
	s_waitcnt lgkmcnt(12)
	v_add_f32_e32 v237, v237, v97
	s_waitcnt lgkmcnt(11)
	v_add_f32_e32 v246, v246, v106
	s_waitcnt lgkmcnt(10)
	v_add_f32_e32 v238, v238, v98
	s_waitcnt lgkmcnt(9)
	v_add_f32_e32 v247, v247, v107
	s_waitcnt lgkmcnt(8)
	v_add_f32_e32 v239, v239, v99
	s_waitcnt lgkmcnt(7)
	v_add_f32_e32 v248, v248, v108
	s_waitcnt lgkmcnt(6)
	v_add_f32_e32 v240, v240, v100
	s_waitcnt lgkmcnt(5)
	v_add_f32_e32 v249, v249, v109
	s_waitcnt lgkmcnt(4)
	v_add_f32_e32 v241, v241, v101
	s_waitcnt lgkmcnt(3)
	v_add_f32_e32 v250, v250, v110
	s_waitcnt lgkmcnt(2)
	v_add_f32_e32 v242, v242, v102
	s_waitcnt lgkmcnt(1)
	v_add_f32_e32 v251, v251, v111
	s_waitcnt lgkmcnt(0)
	v_add_f32_e32 v243, v243, v103
	ds_bpermute_b32 v104, v49, v244
	ds_bpermute_b32 v96, v49, v236
	ds_bpermute_b32 v105, v49, v245
	ds_bpermute_b32 v97, v49, v237
	ds_bpermute_b32 v106, v49, v246
	ds_bpermute_b32 v98, v49, v238
	ds_bpermute_b32 v107, v49, v247
	ds_bpermute_b32 v99, v49, v239
	ds_bpermute_b32 v108, v49, v248
	ds_bpermute_b32 v100, v49, v240
	ds_bpermute_b32 v109, v49, v249
	ds_bpermute_b32 v101, v49, v241
	ds_bpermute_b32 v110, v49, v250
	ds_bpermute_b32 v102, v49, v242
	ds_bpermute_b32 v111, v49, v251
	ds_bpermute_b32 v103, v49, v243
	s_waitcnt lgkmcnt(15)
	v_add_f32_e32 v244, v244, v104
	s_waitcnt lgkmcnt(14)
	v_add_f32_e32 v236, v236, v96
	s_waitcnt lgkmcnt(13)
	v_add_f32_e32 v245, v245, v105
	s_waitcnt lgkmcnt(12)
	v_add_f32_e32 v237, v237, v97
	s_waitcnt lgkmcnt(11)
	v_add_f32_e32 v246, v246, v106
	s_waitcnt lgkmcnt(10)
	v_add_f32_e32 v238, v238, v98
	s_waitcnt lgkmcnt(9)
	v_add_f32_e32 v247, v247, v107
	s_waitcnt lgkmcnt(8)
	v_add_f32_e32 v239, v239, v99
	s_waitcnt lgkmcnt(7)
	v_add_f32_e32 v248, v248, v108
	s_waitcnt lgkmcnt(6)
	v_add_f32_e32 v240, v240, v100
	s_waitcnt lgkmcnt(5)
	v_add_f32_e32 v249, v249, v109
	s_waitcnt lgkmcnt(4)
	v_add_f32_e32 v241, v241, v101
	s_waitcnt lgkmcnt(3)
	v_add_f32_e32 v250, v250, v110
	s_waitcnt lgkmcnt(2)
	v_add_f32_e32 v242, v242, v102
	s_waitcnt lgkmcnt(1)
	v_add_f32_e32 v251, v251, v111
	s_waitcnt lgkmcnt(0)
	v_add_f32_e32 v243, v243, v103
	ds_bpermute_b32 v104, v50, v244
	ds_bpermute_b32 v96, v50, v236
	ds_bpermute_b32 v105, v50, v245
	ds_bpermute_b32 v97, v50, v237
	ds_bpermute_b32 v106, v50, v246
	ds_bpermute_b32 v98, v50, v238
	ds_bpermute_b32 v107, v50, v247
	ds_bpermute_b32 v99, v50, v239
	ds_bpermute_b32 v108, v50, v248
	ds_bpermute_b32 v100, v50, v240
	ds_bpermute_b32 v109, v50, v249
	ds_bpermute_b32 v101, v50, v241
	ds_bpermute_b32 v110, v50, v250
	ds_bpermute_b32 v102, v50, v242
	ds_bpermute_b32 v111, v50, v251
	ds_bpermute_b32 v103, v50, v243
	s_waitcnt lgkmcnt(15)
	v_add_f32_e32 v244, v244, v104
	s_waitcnt lgkmcnt(14)
	v_add_f32_e32 v236, v236, v96
	s_waitcnt lgkmcnt(13)
; DI unsigned pk2(float lo, float hi) { const f32x2 v = {lo, hi}; const hwbf16x2 b = __builtin_convertvector(v, hwbf16x2); return __builtin_bit_cast(unsigned, b); }
; DI float frsq(float x) { return __builtin_amdgcn_rsqf(x); }
; DI void postproj_tile(const Params& p, LAS unsigned char* lds, int tile, int tid, int lane, int wave) {
;     ...
;         sq = wave_sum(sq);
;         const u32x2 c2 = *(const u32x2*)(pr + 512 + 4 * lane);
;         float sk = 0.f;
;         { float f; f = bflo(c2.x); sk += f * f; f = bfhi(c2.x); sk += f * f; f = bflo(c2.y); sk += f * f; f = bfhi(c2.y); sk += f * f; }
;         sk = wave_sum(sk);
;         if (lane == 0) { RSQ[tok] = frsq(sq * (1.0f / 512.0f) + 1e-6f); RSKV[tok] = frsq(sk * (1.0f / 256.0f) + 1e-6f); }
;         if (lane < 32) {
;             const float x1 = bf2f(pr[768 + lane]), x2 = bf2f(pr[800 + lane]);
;             const float cs = COS[s * 32 + lane], sn = SIN[s * 32 + lane];
;             *(unsigned*)(KROPE + (size_t)tok * 64 + 2 * lane) = pk2(x1 * cs - x2 * sn, x1 * sn + x2 * cs);
	v_add_f32_e32 v245, v245, v105
	s_waitcnt lgkmcnt(12)
	v_add_f32_e32 v237, v237, v97
	s_waitcnt lgkmcnt(11)
	v_add_f32_e32 v246, v246, v106
	s_waitcnt lgkmcnt(10)
	v_add_f32_e32 v238, v238, v98
	s_waitcnt lgkmcnt(9)
	v_add_f32_e32 v247, v247, v107
	s_waitcnt lgkmcnt(8)
	v_add_f32_e32 v239, v239, v99
	s_waitcnt lgkmcnt(7)
	v_add_f32_e32 v248, v248, v108
	s_waitcnt lgkmcnt(6)
	v_add_f32_e32 v240, v240, v100
	s_waitcnt lgkmcnt(5)
	v_add_f32_e32 v249, v249, v109
	s_waitcnt lgkmcnt(4)
	v_add_f32_e32 v241, v241, v101
	s_waitcnt lgkmcnt(3)
	v_add_f32_e32 v250, v250, v110
	s_waitcnt lgkmcnt(2)
	v_add_f32_e32 v242, v242, v102
	s_waitcnt lgkmcnt(1)
	v_add_f32_e32 v251, v251, v111
	s_waitcnt lgkmcnt(0)
	v_add_f32_e32 v243, v243, v103
	ds_bpermute_b32 v104, v51, v244
	ds_bpermute_b32 v96, v51, v236
	ds_bpermute_b32 v105, v51, v245
	ds_bpermute_b32 v97, v51, v237
	ds_bpermute_b32 v106, v51, v246
	ds_bpermute_b32 v98, v51, v238
	ds_bpermute_b32 v107, v51, v247
	ds_bpermute_b32 v99, v51, v239
	ds_bpermute_b32 v108, v51, v248
	ds_bpermute_b32 v100, v51, v240
	ds_bpermute_b32 v109, v51, v249
	ds_bpermute_b32 v101, v51, v241
	ds_bpermute_b32 v110, v51, v250
	ds_bpermute_b32 v102, v51, v242
	ds_bpermute_b32 v111, v51, v251
	ds_bpermute_b32 v103, v51, v243
	s_waitcnt lgkmcnt(15)
	v_add_f32_e32 v244, v244, v104
	s_waitcnt lgkmcnt(14)
	v_add_f32_e32 v236, v236, v96
	s_waitcnt lgkmcnt(13)
	v_add_f32_e32 v245, v245, v105
	s_waitcnt lgkmcnt(12)
	v_add_f32_e32 v237, v237, v97
	s_waitcnt lgkmcnt(11)
	v_add_f32_e32 v246, v246, v106
	s_waitcnt lgkmcnt(10)
	v_add_f32_e32 v238, v238, v98
	s_waitcnt lgkmcnt(9)
	v_add_f32_e32 v247, v247, v107
	s_waitcnt lgkmcnt(8)
	v_add_f32_e32 v239, v239, v99
	s_waitcnt lgkmcnt(7)
	v_add_f32_e32 v248, v248, v108
	s_waitcnt lgkmcnt(6)
	v_add_f32_e32 v240, v240, v100
	s_waitcnt lgkmcnt(5)
	v_add_f32_e32 v249, v249, v109
	s_waitcnt lgkmcnt(4)
	v_add_f32_e32 v241, v241, v101
	s_waitcnt lgkmcnt(3)
	v_add_f32_e32 v250, v250, v110
	s_waitcnt lgkmcnt(2)
	v_add_f32_e32 v242, v242, v102
	s_waitcnt lgkmcnt(1)
	v_add_f32_e32 v251, v251, v111
	s_waitcnt lgkmcnt(0)
	v_add_f32_e32 v243, v243, v103
	ds_bpermute_b32 v104, v52, v244
	ds_bpermute_b32 v96, v52, v236
	ds_bpermute_b32 v105, v52, v245
	ds_bpermute_b32 v97, v52, v237
	ds_bpermute_b32 v106, v52, v246
	ds_bpermute_b32 v98, v52, v238
	ds_bpermute_b32 v107, v52, v247
	ds_bpermute_b32 v99, v52, v239
	ds_bpermute_b32 v108, v52, v248
	ds_bpermute_b32 v100, v52, v240
	ds_bpermute_b32 v109, v52, v249
	ds_bpermute_b32 v101, v52, v241
	ds_bpermute_b32 v110, v52, v250
	ds_bpermute_b32 v102, v52, v242
	ds_bpermute_b32 v111, v52, v251
	ds_bpermute_b32 v103, v52, v243
	s_waitcnt lgkmcnt(15)
	v_add_f32_e32 v244, v244, v104
	s_waitcnt lgkmcnt(14)
	v_add_f32_e32 v236, v236, v96
	s_waitcnt lgkmcnt(13)
	v_add_f32_e32 v245, v245, v105
	s_waitcnt lgkmcnt(12)
	v_add_f32_e32 v237, v237, v97
	s_waitcnt lgkmcnt(11)
	v_add_f32_e32 v246, v246, v106
	s_waitcnt lgkmcnt(10)
	v_add_f32_e32 v238, v238, v98
	s_waitcnt lgkmcnt(9)
	v_add_f32_e32 v247, v247, v107
	s_waitcnt lgkmcnt(8)
	v_add_f32_e32 v239, v239, v99
	s_waitcnt lgkmcnt(7)
	v_add_f32_e32 v248, v248, v108
	s_waitcnt lgkmcnt(6)
	v_add_f32_e32 v240, v240, v100
	s_waitcnt lgkmcnt(5)
	v_add_f32_e32 v249, v249, v109
	s_waitcnt lgkmcnt(4)
	v_add_f32_e32 v241, v241, v101
	s_waitcnt lgkmcnt(3)
	v_add_f32_e32 v250, v250, v110
	s_waitcnt lgkmcnt(2)
	v_add_f32_e32 v242, v242, v102
	s_waitcnt lgkmcnt(1)
	v_add_f32_e32 v251, v251, v111
	s_waitcnt lgkmcnt(0)
	v_add_f32_e32 v243, v243, v103
	v_fmamk_f32 v236, v236, 0x3b000000, v63
	v_fmamk_f32 v244, v244, 0x3b800000, v63
	v_fmamk_f32 v237, v237, 0x3b000000, v63
	v_fmamk_f32 v245, v245, 0x3b800000, v63
	v_fmamk_f32 v238, v238, 0x3b000000, v63
	v_fmamk_f32 v246, v246, 0x3b800000, v63
	v_fmamk_f32 v239, v239, 0x3b000000, v63
	v_fmamk_f32 v247, v247, 0x3b800000, v63
	v_fmamk_f32 v240, v240, 0x3b000000, v63
	v_fmamk_f32 v248, v248, 0x3b800000, v63
	v_fmamk_f32 v241, v241, 0x3b000000, v63
	v_fmamk_f32 v249, v249, 0x3b800000, v63
	v_fmamk_f32 v242, v242, 0x3b000000, v63
	v_fmamk_f32 v250, v250, 0x3b800000, v63
	v_fmamk_f32 v243, v243, 0x3b000000, v63
	v_fmamk_f32 v251, v251, 0x3b800000, v63
	v_rsq_f32_e32 v236, v236
	v_rsq_f32_e32 v244, v244
	v_rsq_f32_e32 v237, v237
	v_rsq_f32_e32 v245, v245
	v_rsq_f32_e32 v238, v238
	v_rsq_f32_e32 v246, v246
	v_rsq_f32_e32 v239, v239
	v_rsq_f32_e32 v247, v247
	v_rsq_f32_e32 v240, v240
	v_rsq_f32_e32 v248, v248
	v_rsq_f32_e32 v241, v241
	v_rsq_f32_e32 v249, v249
	v_rsq_f32_e32 v242, v242
	v_rsq_f32_e32 v250, v250
	v_rsq_f32_e32 v243, v243
	v_rsq_f32_e32 v251, v251
	s_add_u32 s30, s62, s24
	s_addc_u32 s31, s63, s25
	s_and_saveexec_b64 s[26:27], s[4:5]
	v_lshl_add_u64 v[120:121], s[62:63], 0, v[40:41]
	s_waitcnt vmcnt(44)
	v_lshlrev_b32_e32 v73, 16, v194
	v_lshlrev_b32_e32 v72, 16, v186
	v_pk_mul_f32 v[68:69], v[202:203], v[72:73] op_sel:[0,1] op_sel_hi:[0,0]
	s_nop 0
	v_pk_fma_f32 v[74:75], v[218:219], v[72:73], v[68:69] neg_lo:[0,0,1] neg_hi:[0,0,1]
	v_pk_fma_f32 v[68:69], v[218:219], v[72:73], v[68:69] op_sel_hi:[0,1,1]
	v_cvt_pk_bf16_f32 v112, v74, v69
	s_waitcnt vmcnt(40)
; DI unsigned pk2(float lo, float hi) { const f32x2 v = {lo, hi}; const hwbf16x2 b = __builtin_convertvector(v, hwbf16x2); return __builtin_bit_cast(unsigned, b); }
; DI float frsq(float x) { return __builtin_amdgcn_rsqf(x); }
; DI void postproj_tile(const Params& p, LAS unsigned char* lds, int tile, int tid, int lane, int wave) {
;     ...
;         if (lane == 0) { RSQ[tok] = frsq(sq * (1.0f / 512.0f) + 1e-6f); RSKV[tok] = frsq(sk * (1.0f / 256.0f) + 1e-6f); }
;         if (lane < 32) {
;             const float x1 = bf2f(pr[768 + lane]), x2 = bf2f(pr[800 + lane]);
;             const float cs = COS[s * 32 + lane], sn = SIN[s * 32 + lane];
;             *(unsigned*)(KROPE + (size_t)tok * 64 + 2 * lane) = pk2(x1 * cs - x2 * sn, x1 * sn + x2 * cs);
;         }
;         const int g = lane >> 5, d = (2 * lane) & 63;
;         const unsigned kc2 = *(const unsigned*)(pr + 1856 + 2 * lane);
;         *(unsigned*)(KCg + ((size_t)((b * 2 + g) * S_ + s)) * 64 + d) = kc2;
;         const unsigned vc2 = *(const unsigned*)(pr + 1984 + 2 * lane);
;         *(unsigned*)(VCg + ((size_t)((b * 2 + g) * S_ + s)) * 64 + d) = vc2;
	v_lshlrev_b32_e32 v73, 16, v195
	v_lshlrev_b32_e32 v72, 16, v187
	v_pk_mul_f32 v[68:69], v[204:205], v[72:73] op_sel:[0,1] op_sel_hi:[0,0]
	s_nop 0
	v_pk_fma_f32 v[74:75], v[220:221], v[72:73], v[68:69] neg_lo:[0,0,1] neg_hi:[0,0,1]
	v_pk_fma_f32 v[68:69], v[220:221], v[72:73], v[68:69] op_sel_hi:[0,1,1]
	v_cvt_pk_bf16_f32 v113, v74, v69
	s_waitcnt vmcnt(36)
	v_lshlrev_b32_e32 v73, 16, v196
	v_lshlrev_b32_e32 v72, 16, v188
	v_pk_mul_f32 v[68:69], v[206:207], v[72:73] op_sel:[0,1] op_sel_hi:[0,0]
	s_nop 0
	v_pk_fma_f32 v[74:75], v[222:223], v[72:73], v[68:69] neg_lo:[0,0,1] neg_hi:[0,0,1]
	v_pk_fma_f32 v[68:69], v[222:223], v[72:73], v[68:69] op_sel_hi:[0,1,1]
	v_cvt_pk_bf16_f32 v114, v74, v69
	s_waitcnt vmcnt(32)
	v_lshlrev_b32_e32 v73, 16, v197
	v_lshlrev_b32_e32 v72, 16, v189
	v_pk_mul_f32 v[68:69], v[208:209], v[72:73] op_sel:[0,1] op_sel_hi:[0,0]
	s_nop 0
	v_pk_fma_f32 v[74:75], v[224:225], v[72:73], v[68:69] neg_lo:[0,0,1] neg_hi:[0,0,1]
	v_pk_fma_f32 v[68:69], v[224:225], v[72:73], v[68:69] op_sel_hi:[0,1,1]
	v_cvt_pk_bf16_f32 v115, v74, v69
	s_waitcnt vmcnt(28)
	v_lshlrev_b32_e32 v73, 16, v198
	v_lshlrev_b32_e32 v72, 16, v190
	v_pk_mul_f32 v[68:69], v[210:211], v[72:73] op_sel:[0,1] op_sel_hi:[0,0]
	s_nop 0
	v_pk_fma_f32 v[74:75], v[226:227], v[72:73], v[68:69] neg_lo:[0,0,1] neg_hi:[0,0,1]
	v_pk_fma_f32 v[68:69], v[226:227], v[72:73], v[68:69] op_sel_hi:[0,1,1]
	v_cvt_pk_bf16_f32 v116, v74, v69
	s_waitcnt vmcnt(24)
	v_lshlrev_b32_e32 v73, 16, v199
	v_lshlrev_b32_e32 v72, 16, v191
	v_pk_mul_f32 v[68:69], v[212:213], v[72:73] op_sel:[0,1] op_sel_hi:[0,0]
	s_nop 0
	v_pk_fma_f32 v[74:75], v[228:229], v[72:73], v[68:69] neg_lo:[0,0,1] neg_hi:[0,0,1]
	v_pk_fma_f32 v[68:69], v[228:229], v[72:73], v[68:69] op_sel_hi:[0,1,1]
	v_cvt_pk_bf16_f32 v117, v74, v69
	s_waitcnt vmcnt(20)
	v_lshlrev_b32_e32 v73, 16, v200
	v_lshlrev_b32_e32 v72, 16, v192
	v_pk_mul_f32 v[68:69], v[214:215], v[72:73] op_sel:[0,1] op_sel_hi:[0,0]
	s_nop 0
	v_pk_fma_f32 v[74:75], v[230:231], v[72:73], v[68:69] neg_lo:[0,0,1] neg_hi:[0,0,1]
	v_pk_fma_f32 v[68:69], v[230:231], v[72:73], v[68:69] op_sel_hi:[0,1,1]
	v_cvt_pk_bf16_f32 v118, v74, v69
	s_waitcnt vmcnt(16)
	v_lshlrev_b32_e32 v73, 16, v201
	v_lshlrev_b32_e32 v72, 16, v193
	v_pk_mul_f32 v[68:69], v[216:217], v[72:73] op_sel:[0,1] op_sel_hi:[0,0]
	s_nop 0
	v_pk_fma_f32 v[74:75], v[232:233], v[72:73], v[68:69] neg_lo:[0,0,1] neg_hi:[0,0,1]
	v_pk_fma_f32 v[68:69], v[232:233], v[72:73], v[68:69] op_sel_hi:[0,1,1]
	v_cvt_pk_bf16_f32 v119, v74, v69
	s_nop 0
	global_store_dword v[120:121], v112, off offset:0
	global_store_dword v[120:121], v113, off offset:128
	global_store_dword v[120:121], v114, off offset:256
	global_store_dword v[120:121], v115, off offset:384
	global_store_dword v[120:121], v116, off offset:512
	global_store_dword v[120:121], v117, off offset:640
	global_store_dword v[120:121], v118, off offset:768
	global_store_dword v[120:121], v119, off offset:896
	s_or_b64 exec, exec, s[26:27]
	s_and_saveexec_b64 s[26:27], s[2:3]
	global_store_dword v64, v236, s[30:31] offset:0
	global_store_dword v65, v244, s[30:31] offset:0
	global_store_dword v64, v237, s[30:31] offset:4
	global_store_dword v65, v245, s[30:31] offset:4
	global_store_dword v64, v238, s[30:31] offset:8
	global_store_dword v65, v246, s[30:31] offset:8
	global_store_dword v64, v239, s[30:31] offset:12
	global_store_dword v65, v247, s[30:31] offset:12
	global_store_dword v64, v240, s[30:31] offset:16
	global_store_dword v65, v248, s[30:31] offset:16
	global_store_dword v64, v241, s[30:31] offset:20
	global_store_dword v65, v249, s[30:31] offset:20
	global_store_dword v64, v242, s[30:31] offset:24
	global_store_dword v65, v250, s[30:31] offset:24
	global_store_dword v64, v243, s[30:31] offset:28
	global_store_dword v65, v251, s[30:31] offset:28
	s_or_b64 exec, exec, s[26:27]
	v_lshl_add_u64 v[70:71], s[62:63], 0, v[42:43]
	s_nop 0
	v_add_co_u32_e32 v72, vcc, 0x2f400000, v70
	s_nop 1
	v_addc_co_u32_e32 v73, vcc, 0, v71, vcc
	v_add_co_u32_e32 v68, vcc, 0x2fc10000, v70
	s_nop 1
	v_addc_co_u32_e32 v69, vcc, 0, v71, vcc
	s_waitcnt vmcnt(24)
	global_store_dword v[72:73], v170, off offset:0
	global_store_dword v[68:69], v178, off offset:0
	global_store_dword v[72:73], v171, off offset:128
	global_store_dword v[68:69], v179, off offset:128
	global_store_dword v[72:73], v172, off offset:256
	global_store_dword v[68:69], v180, off offset:256
	global_store_dword v[72:73], v173, off offset:384
	global_store_dword v[68:69], v181, off offset:384
	global_store_dword v[72:73], v174, off offset:512
	global_store_dword v[68:69], v182, off offset:512
	global_store_dword v[72:73], v175, off offset:640
	global_store_dword v[68:69], v183, off offset:640
	global_store_dword v[72:73], v176, off offset:768
	global_store_dword v[68:69], v184, off offset:768
	global_store_dword v[72:73], v177, off offset:896
	global_store_dword v[68:69], v185, off offset:896
	s_branch .LBB0_271
